# tile placement V: 300 FFN2-down conversion tiles moved from the P11 tail (WGs>=172) to the P7 retention WGs (tc2 500 tiles, tc8 404)
# speedup vs baseline: 1.0024x; 1.0024x over previous
; __device__ __forceinline__ void tconv_list(const float* wg, const float* wu, const float* wd, const float* win, const float* wout, unsigned char* ws, const int ntiles, LAS float* t, const int wv) {
;     ...
;     for (; i < ntiles; i += G) {
;         const TDesc d = tconv_desc(wg, wu, wd, win, wout, ws, i);
;         { const TDesc dn = tconv_desc(wg, wu, wd, win, wout, ws, i + G < ntiles ? i + G : i);
; #pragma unroll
;             for (int e = 0; e < 8; ++e) { const int idx = e * 512 + tid, r = idx >> 6, c = idx & 63; nxt[e] = __builtin_nontemporal_load(dn.W + (size_t)(dn.k0 + r) * dn.N + dn.n0 + c); } }
.Ltc2_loop:
	s_add_u32 s4, s4, 128
	s_cmp_lt_u32 s4, 1708
	s_cselect_b32 s31, 1, 0
	s_cbranch_scc0 .Ltc2_nonexta
	v_writelane_b32 v40, s8, 32
	v_writelane_b32 v40, s9, 33
	s_cmp_lt_u32 s4, 704
	s_cbranch_scc0 .Ltc2_seg1_1
	s_mov_b32 s7, s4
	s_and_b32 s8, s7, 15
	s_lshr_b32 s9, s7, 4
	s_mul_i32 s7, s8, 720896
	s_lshl_b32 s29, s9, 8
	s_add_u32 s7, s7, s29
	s_mul_i32 s29, s28, 11264
	s_add_u32 s7, s7, s29
	s_add_u32 s10, s18, s7
	s_addc_u32 s11, s19, 0
	s_lshr_b32 s7, s9, 1
	s_lshl_b32 s7, s7, 8
	s_and_b32 s29, s9, 1
	s_lshl_b32 s29, s29, 6
	s_add_u32 s7, s7, s29
	s_mul_i32 s7, s7, 2048
	s_lshl_b32 s29, s8, 7
	s_add_u32 s7, s7, s29
	s_mul_i32 s29, s28, 4096
	s_add_u32 s7, s7, s29
	s_add_u32 s12, s26, 0x2100000
	s_addc_u32 s13, s27, 0
	s_add_u32 s12, s12, s7
	s_addc_u32 s13, s13, 0
	s_mov_b32 s14, 90112
	s_mov_b32 s15, 32768
	s_movk_i32 s16, 2048
	s_branch .Ltc2_segend_1

; __device__ __forceinline__ unsigned cvt_pk_bf16(float lo, float hi) { const f32x2_t v = {lo, hi}; const bf16x2_t b = __builtin_convertvector(v, bf16x2_t); return __builtin_bit_cast(unsigned, b); }
; __device__ __forceinline__ void tconv_list(const float* wg, const float* wu, const float* wd, const float* win, const float* wout, unsigned char* ws, const int ntiles, LAS float* t, const int wv) {
;     ...
; #pragma unroll
;         for (int e = 0; e < 8; ++e) { const int idx = e * 512 + tid, r = idx >> 6, c = idx & 63; t[r * 65 + c] = cur[e]; }
;         __syncthreads();
; #pragma unroll
;         for (int e = 0; e < 4; ++e) { const int idx = e * 512 + tid, n = idx >> 5, kp = idx & 31;
;             const unsigned w = pg8::cvt_pk_bf16(t[(2 * kp) * 65 + n], t[(2 * kp + 1) * 65 + n]);
;             *(unsigned*)(d.Bt + (size_t)(d.brow0 + n) * d.K + d.k0 + 2 * kp) = w; }
;         __syncthreads();
; #pragma unroll
;         for (int e = 0; e < 8; ++e) cur[e] = nxt[e];
.Ltc2_havea:
	ds_write_b32 v5, v8 offset:0
	ds_write_b32 v5, v9 offset:2080
	ds_write_b32 v5, v10 offset:4160
	ds_write_b32 v5, v11 offset:6240
	ds_write_b32 v5, v12 offset:8320
	ds_write_b32 v5, v13 offset:10400
	ds_write_b32 v5, v14 offset:12480
	ds_write_b32 v5, v15 offset:14560
	v_mad_u32_u24 v4, v2, s30, v3
	s_waitcnt lgkmcnt(0)
	s_barrier
	ds_read2_b32 v[24:25], v6 offset0:0 offset1:65
	ds_read2_b32 v[26:27], v6 offset0:16 offset1:81
	ds_read2_b32 v[28:29], v6 offset0:32 offset1:97
	ds_read2_b32 v[30:31], v6 offset0:48 offset1:113
	s_waitcnt lgkmcnt(3)
	v_cvt_pk_bf16_f32 v32, v24, v25
	s_waitcnt lgkmcnt(2)
	v_cvt_pk_bf16_f32 v33, v26, v27
	s_waitcnt lgkmcnt(1)
	v_cvt_pk_bf16_f32 v34, v28, v29
	s_waitcnt lgkmcnt(0)
	v_cvt_pk_bf16_f32 v35, v30, v31
	global_store_dword v4, v32, s[8:9]
	s_add_u32 s8, s8, s17
	s_addc_u32 s9, s9, 0
	global_store_dword v4, v33, s[8:9]
	s_add_u32 s8, s8, s17
	s_addc_u32 s9, s9, 0
	global_store_dword v4, v34, s[8:9]
	s_add_u32 s8, s8, s17
	s_addc_u32 s9, s9, 0
	global_store_dword v4, v35, s[8:9]
	s_barrier
	s_cmp_eq_u32 s31, 0
	s_cbranch_scc1 .Ltc2_done
	s_mov_b32 s17, s15
	s_mov_b32 s30, s16
	s_mov_b64 s[8:9], s[12:13]
	s_add_u32 s4, s4, 128
	s_cmp_lt_u32 s4, 1708
	s_cselect_b32 s31, 1, 0
	s_cbranch_scc0 .Ltc2_nonextb
	v_writelane_b32 v40, s8, 32
	v_writelane_b32 v40, s9, 33
	s_cmp_lt_u32 s4, 704
	s_cbranch_scc0 .Ltc2_seg1_2
	s_mov_b32 s7, s4
	s_and_b32 s8, s7, 15
	s_lshr_b32 s9, s7, 4
	s_mul_i32 s7, s8, 720896
	s_lshl_b32 s29, s9, 8
	s_add_u32 s7, s7, s29
	s_mul_i32 s29, s28, 11264
	s_add_u32 s7, s7, s29
	s_add_u32 s10, s18, s7
	s_addc_u32 s11, s19, 0
	s_lshr_b32 s7, s9, 1
	s_lshl_b32 s7, s7, 8
	s_and_b32 s29, s9, 1
	s_lshl_b32 s29, s29, 6
	s_add_u32 s7, s7, s29
	s_mul_i32 s7, s7, 2048
	s_lshl_b32 s29, s8, 7
	s_add_u32 s7, s7, s29
	s_mul_i32 s29, s28, 4096
	s_add_u32 s7, s7, s29
	s_add_u32 s12, s26, 0x2100000
	s_addc_u32 s13, s27, 0
	s_add_u32 s12, s12, s7
	s_addc_u32 s13, s13, 0
	s_mov_b32 s14, 90112
	s_mov_b32 s15, 32768
	s_movk_i32 s16, 2048
	s_branch .Ltc2_segend_2

; __device__ __forceinline__ int fresh_tid(int wv) { int l; asm volatile("v_mbcnt_lo_u32_b32 %0, -1, 0\n\tv_mbcnt_hi_u32_b32 %0, -1, %0" : "=v"(l)); return wv * 64 + l; }
; #define LAS __attribute__((address_space(3)))
; __device__ __forceinline__ void tconv_list(const float* wg, const float* wu, const float* wd, const float* win, const float* wout, unsigned char* ws, const int ntiles, LAS float* t, const int wv) {
;     const int tid = fresh_tid(wv); const int G = gridDim.x;
;     float cur[8], nxt[8];
;     int i = blockIdx.x;
;     if (i < ntiles) { const TDesc d = tconv_desc(wg, wu, wd, win, wout, ws, i);
; #pragma unroll
;         for (int e = 0; e < 8; ++e) { const int idx = e * 512 + tid, r = idx >> 6, c = idx & 63; cur[e] = __builtin_nontemporal_load(d.W + (size_t)(d.k0 + r) * d.N + d.n0 + c); } }
.LBB0_1013:
	s_cmp_lt_u32 s2, 172
	s_cbranch_scc1 .Ltc8_skip
	v_writelane_b32 v40, s4, 4
	v_writelane_b32 v40, s5, 5
	v_writelane_b32 v40, s6, 6
	v_writelane_b32 v40, s7, 7
	v_writelane_b32 v40, s8, 8
	v_writelane_b32 v40, s9, 9
	v_writelane_b32 v40, s10, 10
	v_writelane_b32 v40, s11, 11
	v_writelane_b32 v40, s12, 12
	v_writelane_b32 v40, s13, 13
	v_writelane_b32 v40, s14, 14
	v_writelane_b32 v40, s15, 15
	v_writelane_b32 v40, s16, 16
	v_writelane_b32 v40, s17, 17
	v_writelane_b32 v40, s18, 18
	v_writelane_b32 v40, s19, 19
	v_writelane_b32 v40, s20, 20
	v_writelane_b32 v40, s21, 21
	v_writelane_b32 v40, s22, 22
	v_writelane_b32 v40, s23, 23
	v_writelane_b32 v40, s24, 24
	v_writelane_b32 v40, s25, 25
	v_writelane_b32 v40, s26, 26
	v_writelane_b32 v40, s27, 27
	v_writelane_b32 v40, s28, 28
	v_writelane_b32 v40, s29, 29
	v_writelane_b32 v40, s30, 30
	v_writelane_b32 v40, s31, 31
	s_load_dwordx2 s[24:25], s[38:39], 0xd8
	s_load_dwordx2 s[26:27], s[38:39], 0xd0
	s_load_dwordx2 s[18:19], s[38:39], 0xb8
	s_load_dwordx2 s[20:21], s[38:39], 0xc0
	s_load_dwordx2 s[22:23], s[38:39], 0xc8
	v_mbcnt_lo_u32_b32 v0, -1, 0
	v_mbcnt_hi_u32_b32 v0, -1, v0
	s_lshr_b32 s28, s33, 6
	v_lshlrev_b32_e32 v1, 2, v0
	v_lshrrev_b32_e32 v2, 5, v0
	v_and_b32_e32 v3, 31, v0
	s_mul_i32 s7, s28, 260
	v_add_u32_e32 v5, s7, v1
	v_mul_u32_u24_e32 v6, 0x208, v3
	s_lshl_b32 s7, s28, 3
	v_lshl_add_u32 v6, v2, 2, v6
	v_add_u32_e32 v6, s7, v6
	v_lshlrev_b32_e32 v3, 2, v3
	s_sub_u32 s4, s2, 172
	s_add_u32 s4, s4, 1708
	s_waitcnt lgkmcnt(0)
	s_cmp_lt_u32 s4, 704
	s_cbranch_scc0 .Ltc8_seg1_0
	s_mov_b32 s7, s4
	s_and_b32 s8, s7, 15
	s_lshr_b32 s9, s7, 4
	s_mul_i32 s7, s8, 720896
	s_lshl_b32 s29, s9, 8
	s_add_u32 s7, s7, s29
	s_mul_i32 s29, s28, 11264
	s_add_u32 s7, s7, s29
	s_add_u32 s10, s18, s7
	s_addc_u32 s11, s19, 0
	s_lshr_b32 s7, s9, 1
	s_lshl_b32 s7, s7, 8
	s_and_b32 s29, s9, 1
	s_lshl_b32 s29, s29, 6
	s_add_u32 s7, s7, s29
	s_mul_i32 s7, s7, 2048
	s_lshl_b32 s29, s8, 7
	s_add_u32 s7, s7, s29
	s_mul_i32 s29, s28, 4096
	s_add_u32 s7, s7, s29
	s_add_u32 s12, s26, 0x2100000
	s_addc_u32 s13, s27, 0
	s_add_u32 s12, s12, s7
	s_addc_u32 s13, s13, 0
	s_mov_b32 s14, 90112
	s_mov_b32 s15, 32768
	s_movk_i32 s16, 2048
	s_branch .Ltc8_segend_0
